# GMOD EpiMod epilogue: hoist the 4 bias vector loads (were reloaded+waited 32x per tile, serialized with stores)
# baseline (speedup 1.0000x reference)
;     __device__ __forceinline__ void operator()(const AccT& acc, const pg8::Unit& u, int wr, int wc, int fr, int fq) const {
;         const int row0 = u.pm * 256 + wr * 64 + fr, col0 = u.pn * 256 + wc * 32 + 8 * fq;
; #pragma unroll
;         for (int ai = 0; ai < 2; ++ai)
; #pragma unroll
;             for (int m = 0; m < 4; ++m) {
;                 const int row = row0 + ai * 128 + m * 16;
;                 if (row < NSEQ) {
; #pragma unroll
;                     for (int bj = 0; bj < 2; ++bj) {
;                         const int c = col0 + bj * 128; const int l = c / 9216, cc = c - l * 9216;
;                         float* p = O + ((size_t)l * NSEQ + row) * 9216 + cc;
;                         *(f32x4*)p = acc[ai][bj][m][0] + *(const f32x4*)(bias + c);
;                         *(f32x4*)(p + 4) = acc[ai][bj][m][1] + *(const f32x4*)(bias + c + 4);
;                     }
;                 }
;             }
;     }
.LBB0_845:
	v_lshl_add_u32 v144, s20, 8, v3
	s_movk_i32 s11, 0x88
	v_lshl_or_b32 v142, s18, 8, v147
	v_cmp_gt_i32_e32 vcc, s11, v144
	s_mov_b32 s11, 0x38e38e39
	v_mul_hi_i32 v145, v142, s11
	v_or_b32_e32 v165, 0x80, v142
	v_ashrrev_i32_e32 v143, 31, v142
	v_lshrrev_b32_e32 v167, 31, v145
	v_ashrrev_i32_e32 v168, 11, v145
	v_mul_hi_i32 v166, v165, s11
	v_readlane_b32 s50, v251, 2
	v_readlane_b32 s51, v251, 3
	s_nop 3
	v_lshl_add_u64 v[200:201], v[142:143], 2, s[50:51]
	global_load_dwordx4 v[184:187], v[200:201], off
	global_load_dwordx4 v[188:191], v[200:201], off offset:16
	global_load_dwordx4 v[192:195], v[200:201], off offset:512
	global_load_dwordx4 v[196:199], v[200:201], off offset:528
	s_waitcnt vmcnt(0)
	s_and_saveexec_b64 s[18:19], vcc
	s_mov_b32 s13, 0x9000
	s_movk_i32 s20, 0xdc00
	s_cbranch_execz .LBB0_847
	v_add_u32_e32 v148, v168, v167
	v_mul_i32_i24_e32 v172, 0x88, v148
	v_ashrrev_i32_e32 v145, 31, v144
	v_ashrrev_i32_e32 v173, 31, v172
	v_lshl_add_u64 v[172:173], v[172:173], 0, v[144:145]
	v_mov_b64_e32 v[174:175], s[6:7]
	v_readlane_b32 s48, v251, 0
	v_mad_i32_i24 v170, v148, s20, v142
	v_mad_u64_u32 v[176:177], s[22:23], v172, s13, v[174:175]
	v_readlane_b32 s50, v251, 2
	v_readlane_b32 s51, v251, 3
	v_mad_i32_i24 v177, v173, s13, v177
	v_ashrrev_i32_e32 v171, 31, v170
	v_lshl_add_u64 v[178:179], v[142:143], 2, s[50:51]
	v_lshl_add_u64 v[176:177], v[170:171], 2, v[176:177]
	v_readlane_b32 s49, v251, 1
	v_readlane_b32 s52, v251, 4
	v_readlane_b32 s53, v251, 5
	v_readlane_b32 s54, v251, 6
	v_readlane_b32 s55, v251, 7
	v_readlane_b32 s56, v251, 8
	v_readlane_b32 s57, v251, 9
	v_readlane_b32 s58, v251, 10
	v_readlane_b32 s59, v251, 11
	v_readlane_b32 s60, v251, 12
	v_readlane_b32 s61, v251, 13
	v_readlane_b32 s62, v251, 14
	v_readlane_b32 s63, v251, 15
	v_pk_add_f32 v[130:131], v[130:131], v[186:187]
	v_pk_add_f32 v[128:129], v[128:129], v[184:185]
	global_store_dwordx4 v[176:177], v[128:131], off
	v_pk_add_f32 v[126:127], v[126:127], v[190:191]
	v_pk_add_f32 v[124:125], v[124:125], v[188:189]
	global_store_dwordx4 v[176:177], v[124:127], off offset:16
	s_nop 1
	v_lshrrev_b32_e32 v124, 31, v166
	v_ashrrev_i32_e32 v125, 11, v166
	v_add_u32_e32 v125, v125, v124
	v_mul_i32_i24_e32 v126, 0x88, v125
	v_ashrrev_i32_e32 v127, 31, v126
	v_lshl_add_u64 v[126:127], v[126:127], 0, v[144:145]
	v_mad_i32_i24 v124, v125, s20, v165
	v_mad_u64_u32 v[128:129], s[22:23], v126, s13, v[174:175]
	v_mad_i32_i24 v129, v127, s13, v129
	v_ashrrev_i32_e32 v125, 31, v124
	v_lshl_add_u64 v[128:129], v[124:125], 2, v[128:129]
	v_pk_add_f32 v[122:123], v[122:123], v[194:195]
	v_pk_add_f32 v[120:121], v[120:121], v[192:193]
	global_store_dwordx4 v[128:129], v[120:123], off
	v_pk_add_f32 v[118:119], v[118:119], v[198:199]
	v_pk_add_f32 v[116:117], v[116:117], v[196:197]
	global_store_dwordx4 v[128:129], v[116:119], off offset:16
.LBB0_847:
	s_or_b64 exec, exec, s[18:19]
	s_nop 0
	v_or_b32_e32 v116, 16, v144
	s_movk_i32 s11, 0x88
	v_cmp_gt_i32_e32 vcc, s11, v116
	s_and_saveexec_b64 s[18:19], vcc
	s_cbranch_execz .LBB0_849
	v_add_u32_e32 v119, v168, v167
	v_mul_i32_i24_e32 v120, 0x88, v119
	v_ashrrev_i32_e32 v117, 31, v116
	v_ashrrev_i32_e32 v121, 31, v120
	v_lshl_add_u64 v[120:121], v[120:121], 0, v[116:117]
	v_mov_b64_e32 v[122:123], s[6:7]
	v_readlane_b32 s48, v251, 0
	v_mad_i32_i24 v118, v119, s20, v142
	v_mad_u64_u32 v[124:125], s[22:23], v120, s13, v[122:123]
	v_readlane_b32 s50, v251, 2
	v_readlane_b32 s51, v251, 3
	v_mad_i32_i24 v125, v121, s13, v125
	v_ashrrev_i32_e32 v119, 31, v118
	v_lshl_add_u64 v[126:127], v[142:143], 2, s[50:51]
	v_lshl_add_u64 v[124:125], v[118:119], 2, v[124:125]
	v_readlane_b32 s49, v251, 1
	v_readlane_b32 s52, v251, 4
	v_readlane_b32 s53, v251, 5
	v_readlane_b32 s54, v251, 6
	v_readlane_b32 s55, v251, 7
	v_readlane_b32 s56, v251, 8
	v_readlane_b32 s57, v251, 9
	v_readlane_b32 s58, v251, 10
	v_readlane_b32 s59, v251, 11
	v_readlane_b32 s60, v251, 12
	v_readlane_b32 s61, v251, 13
	v_readlane_b32 s62, v251, 14
	v_readlane_b32 s63, v251, 15
	v_pk_add_f32 v[114:115], v[114:115], v[186:187]
	v_pk_add_f32 v[112:113], v[112:113], v[184:185]
	global_store_dwordx4 v[124:125], v[112:115], off
	v_pk_add_f32 v[110:111], v[110:111], v[190:191]
	v_pk_add_f32 v[108:109], v[108:109], v[188:189]
	global_store_dwordx4 v[124:125], v[108:111], off offset:16
	s_nop 1
	v_lshrrev_b32_e32 v108, 31, v166
	v_ashrrev_i32_e32 v109, 11, v166
	v_add_u32_e32 v109, v109, v108
	v_mul_i32_i24_e32 v110, 0x88, v109
	v_ashrrev_i32_e32 v111, 31, v110
	v_lshl_add_u64 v[110:111], v[110:111], 0, v[116:117]
	v_mad_i32_i24 v108, v109, s20, v165
	v_mad_u64_u32 v[112:113], s[22:23], v110, s13, v[122:123]
	v_mad_i32_i24 v113, v111, s13, v113
	v_ashrrev_i32_e32 v109, 31, v108
	v_lshl_add_u64 v[112:113], v[108:109], 2, v[112:113]
	v_pk_add_f32 v[106:107], v[106:107], v[194:195]
	v_pk_add_f32 v[104:105], v[104:105], v[192:193]
	global_store_dwordx4 v[112:113], v[104:107], off
	v_pk_add_f32 v[102:103], v[102:103], v[198:199]
	v_pk_add_f32 v[100:101], v[100:101], v[196:197]
	global_store_dwordx4 v[112:113], v[100:103], off offset:16
;     __device__ __forceinline__ void operator()(const AccT& acc, const pg8::Unit& u, int wr, int wc, int fr, int fq) const {
;     ...
;         for (int ai = 0; ai < 2; ++ai)
; #pragma unroll
;             for (int m = 0; m < 4; ++m) {
;                 const int row = row0 + ai * 128 + m * 16;
;                 if (row < NSEQ) {
; #pragma unroll
;                     for (int bj = 0; bj < 2; ++bj) {
;                         const int c = col0 + bj * 128; const int l = c / 9216, cc = c - l * 9216;
;                         float* p = O + ((size_t)l * NSEQ + row) * 9216 + cc;
;                         *(f32x4*)p = acc[ai][bj][m][0] + *(const f32x4*)(bias + c);
;                         *(f32x4*)(p + 4) = acc[ai][bj][m][1] + *(const f32x4*)(bias + c + 4);
;                     }
;                 }
;             }
.LBB0_849:
	s_or_b64 exec, exec, s[18:19]
	s_nop 0
	v_or_b32_e32 v100, 32, v144
	v_cmp_gt_i32_e32 vcc, s11, v100
	s_and_saveexec_b64 s[18:19], vcc
	s_cbranch_execz .LBB0_851
	v_add_u32_e32 v103, v168, v167
	v_mul_i32_i24_e32 v104, 0x88, v103
	v_ashrrev_i32_e32 v101, 31, v100
	v_ashrrev_i32_e32 v105, 31, v104
	v_lshl_add_u64 v[104:105], v[104:105], 0, v[100:101]
	v_mov_b64_e32 v[106:107], s[6:7]
	v_readlane_b32 s48, v251, 0
	v_mad_i32_i24 v102, v103, s20, v142
	v_mad_u64_u32 v[108:109], s[22:23], v104, s13, v[106:107]
	v_readlane_b32 s50, v251, 2
	v_readlane_b32 s51, v251, 3
	v_mad_i32_i24 v109, v105, s13, v109
	v_ashrrev_i32_e32 v103, 31, v102
	v_lshl_add_u64 v[110:111], v[142:143], 2, s[50:51]
	v_lshl_add_u64 v[108:109], v[102:103], 2, v[108:109]
	v_readlane_b32 s49, v251, 1
	v_readlane_b32 s52, v251, 4
	v_readlane_b32 s53, v251, 5
	v_readlane_b32 s54, v251, 6
	v_readlane_b32 s55, v251, 7
	v_readlane_b32 s56, v251, 8
	v_readlane_b32 s57, v251, 9
	v_readlane_b32 s58, v251, 10
	v_readlane_b32 s59, v251, 11
	v_readlane_b32 s60, v251, 12
	v_readlane_b32 s61, v251, 13
	v_readlane_b32 s62, v251, 14
	v_readlane_b32 s63, v251, 15
	v_pk_add_f32 v[98:99], v[98:99], v[186:187]
	v_pk_add_f32 v[96:97], v[96:97], v[184:185]
	global_store_dwordx4 v[108:109], v[96:99], off
	v_pk_add_f32 v[94:95], v[94:95], v[190:191]
	v_pk_add_f32 v[92:93], v[92:93], v[188:189]
	global_store_dwordx4 v[108:109], v[92:95], off offset:16
	s_nop 1
	v_lshrrev_b32_e32 v92, 31, v166
	v_ashrrev_i32_e32 v93, 11, v166
	v_add_u32_e32 v93, v93, v92
	v_mul_i32_i24_e32 v94, 0x88, v93
	v_ashrrev_i32_e32 v95, 31, v94
	v_lshl_add_u64 v[94:95], v[94:95], 0, v[100:101]
	v_mad_i32_i24 v92, v93, s20, v165
	v_mad_u64_u32 v[96:97], s[22:23], v94, s13, v[106:107]
	v_mad_i32_i24 v97, v95, s13, v97
	v_ashrrev_i32_e32 v93, 31, v92
	v_lshl_add_u64 v[96:97], v[92:93], 2, v[96:97]
	v_pk_add_f32 v[90:91], v[90:91], v[194:195]
	v_pk_add_f32 v[88:89], v[88:89], v[192:193]
	global_store_dwordx4 v[96:97], v[88:91], off
	v_pk_add_f32 v[86:87], v[86:87], v[198:199]
	v_pk_add_f32 v[84:85], v[84:85], v[196:197]
	global_store_dwordx4 v[96:97], v[84:87], off offset:16
.LBB0_851:
	s_or_b64 exec, exec, s[18:19]
	s_nop 0
	v_or_b32_e32 v84, 48, v144
	v_cmp_gt_i32_e32 vcc, s11, v84
	s_and_saveexec_b64 s[18:19], vcc
	s_cbranch_execz .LBB0_862
	v_add_u32_e32 v87, v168, v167
	v_mul_i32_i24_e32 v88, 0x88, v87
	v_ashrrev_i32_e32 v85, 31, v84
	v_ashrrev_i32_e32 v89, 31, v88
	v_lshl_add_u64 v[88:89], v[88:89], 0, v[84:85]
	v_mov_b64_e32 v[90:91], s[6:7]
	v_readlane_b32 s48, v251, 0
	v_mad_i32_i24 v86, v87, s20, v142
	v_mad_u64_u32 v[92:93], s[22:23], v88, s13, v[90:91]
	v_readlane_b32 s50, v251, 2
	v_readlane_b32 s51, v251, 3
	v_mad_i32_i24 v93, v89, s13, v93
	v_ashrrev_i32_e32 v87, 31, v86
	v_lshl_add_u64 v[94:95], v[142:143], 2, s[50:51]
	v_lshl_add_u64 v[92:93], v[86:87], 2, v[92:93]
	v_readlane_b32 s49, v251, 1
	v_readlane_b32 s52, v251, 4
	v_readlane_b32 s53, v251, 5
	v_readlane_b32 s54, v251, 6
	v_readlane_b32 s55, v251, 7
	v_readlane_b32 s56, v251, 8
	v_readlane_b32 s57, v251, 9
	v_readlane_b32 s58, v251, 10
	v_readlane_b32 s59, v251, 11
	v_readlane_b32 s60, v251, 12
	v_readlane_b32 s61, v251, 13
	v_readlane_b32 s62, v251, 14
	v_readlane_b32 s63, v251, 15
	v_pk_add_f32 v[82:83], v[82:83], v[186:187]
	v_pk_add_f32 v[80:81], v[80:81], v[184:185]
	global_store_dwordx4 v[92:93], v[80:83], off
	v_pk_add_f32 v[78:79], v[78:79], v[190:191]
	v_pk_add_f32 v[76:77], v[76:77], v[188:189]
	global_store_dwordx4 v[92:93], v[76:79], off offset:16
	s_nop 1
	v_lshrrev_b32_e32 v76, 31, v166
	v_ashrrev_i32_e32 v77, 11, v166
	v_add_u32_e32 v77, v77, v76
	v_mul_i32_i24_e32 v78, 0x88, v77
	v_ashrrev_i32_e32 v79, 31, v78
	v_lshl_add_u64 v[78:79], v[78:79], 0, v[84:85]
	v_mad_i32_i24 v76, v77, s20, v165
	v_mad_u64_u32 v[80:81], s[22:23], v78, s13, v[90:91]
	v_mad_i32_i24 v81, v79, s13, v81
	v_ashrrev_i32_e32 v77, 31, v76
	v_lshl_add_u64 v[80:81], v[76:77], 2, v[80:81]
	v_pk_add_f32 v[74:75], v[74:75], v[194:195]
	v_pk_add_f32 v[72:73], v[72:73], v[192:193]
	global_store_dwordx4 v[80:81], v[72:75], off
	v_pk_add_f32 v[70:71], v[70:71], v[198:199]
	v_pk_add_f32 v[68:69], v[68:69], v[196:197]
	global_store_dwordx4 v[80:81], v[68:71], off offset:16
	s_or_b64 exec, exec, s[18:19]
	v_cmp_gt_i32_e32 vcc, 8, v144
	s_and_saveexec_b64 s[18:19], vcc
	s_cbranch_execnz .LBB0_863

;     __device__ __forceinline__ void operator()(const AccT& acc, const pg8::Unit& u, int wr, int wc, int fr, int fq) const {
;     ...
;         for (int ai = 0; ai < 2; ++ai)
; #pragma unroll
;             for (int m = 0; m < 4; ++m) {
;                 const int row = row0 + ai * 128 + m * 16;
;                 if (row < NSEQ) {
; #pragma unroll
;                     for (int bj = 0; bj < 2; ++bj) {
;                         const int c = col0 + bj * 128; const int l = c / 9216, cc = c - l * 9216;
;                         float* p = O + ((size_t)l * NSEQ + row) * 9216 + cc;
;                         *(f32x4*)p = acc[ai][bj][m][0] + *(const f32x4*)(bias + c);
;                         *(f32x4*)(p + 4) = acc[ai][bj][m][1] + *(const f32x4*)(bias + c + 4);
;                     }
;                 }
;             }
.LBB0_854:
	v_add_u32_e32 v53, v168, v167
	v_add_u32_e32 v56, 0x90, v144
	v_mul_i32_i24_e32 v54, 0x88, v53
	v_ashrrev_i32_e32 v57, 31, v56
	v_ashrrev_i32_e32 v55, 31, v54
	v_lshl_add_u64 v[54:55], v[54:55], 0, v[56:57]
	v_mov_b64_e32 v[58:59], s[6:7]
	v_readlane_b32 s48, v251, 0
	v_mad_i32_i24 v52, v53, s20, v142
	v_mad_u64_u32 v[60:61], s[22:23], v54, s13, v[58:59]
	v_readlane_b32 s50, v251, 2
	v_readlane_b32 s51, v251, 3
	v_mad_i32_i24 v61, v55, s13, v61
	v_ashrrev_i32_e32 v53, 31, v52
	v_lshl_add_u64 v[62:63], v[142:143], 2, s[50:51]
	v_lshl_add_u64 v[60:61], v[52:53], 2, v[60:61]
	v_readlane_b32 s49, v251, 1
	v_readlane_b32 s52, v251, 4
	v_readlane_b32 s53, v251, 5
	v_readlane_b32 s54, v251, 6
	v_readlane_b32 s55, v251, 7
	v_readlane_b32 s56, v251, 8
	v_readlane_b32 s57, v251, 9
	v_readlane_b32 s58, v251, 10
	v_readlane_b32 s59, v251, 11
	v_readlane_b32 s60, v251, 12
	v_readlane_b32 s61, v251, 13
	v_readlane_b32 s62, v251, 14
	v_readlane_b32 s63, v251, 15
	v_pk_add_f32 v[50:51], v[50:51], v[186:187]
	v_pk_add_f32 v[48:49], v[48:49], v[184:185]
	global_store_dwordx4 v[60:61], v[48:51], off
	v_pk_add_f32 v[46:47], v[46:47], v[190:191]
	v_pk_add_f32 v[44:45], v[44:45], v[188:189]
	global_store_dwordx4 v[60:61], v[44:47], off offset:16
	s_nop 1
	v_lshrrev_b32_e32 v44, 31, v166
	v_ashrrev_i32_e32 v45, 11, v166
	v_add_u32_e32 v45, v45, v44
	v_mul_i32_i24_e32 v46, 0x88, v45
	v_ashrrev_i32_e32 v47, 31, v46
	v_lshl_add_u64 v[46:47], v[46:47], 0, v[56:57]
	v_mad_i32_i24 v44, v45, s20, v165
	v_mad_u64_u32 v[48:49], s[22:23], v46, s13, v[58:59]
	v_mad_i32_i24 v49, v47, s13, v49
	v_ashrrev_i32_e32 v45, 31, v44
	v_lshl_add_u64 v[48:49], v[44:45], 2, v[48:49]
	v_pk_add_f32 v[42:43], v[42:43], v[194:195]
	v_pk_add_f32 v[40:41], v[40:41], v[192:193]
	global_store_dwordx4 v[48:49], v[40:43], off
	v_pk_add_f32 v[38:39], v[38:39], v[198:199]
	v_pk_add_f32 v[36:37], v[36:37], v[196:197]
	global_store_dwordx4 v[48:49], v[36:39], off offset:16
.LBB0_855:
	s_or_b64 exec, exec, s[18:19]
	s_movk_i32 s11, 0xffe8
	v_cmp_gt_i32_e32 vcc, s11, v144
	s_and_saveexec_b64 s[18:19], vcc
	s_cbranch_execz .LBB0_857
	v_add_u32_e32 v37, v168, v167
	v_add_u32_e32 v40, 0xa0, v144
	v_mul_i32_i24_e32 v38, 0x88, v37
	v_ashrrev_i32_e32 v41, 31, v40
	v_ashrrev_i32_e32 v39, 31, v38
	v_lshl_add_u64 v[38:39], v[38:39], 0, v[40:41]
	v_mov_b64_e32 v[42:43], s[6:7]
	v_readlane_b32 s48, v251, 0
	v_mad_i32_i24 v36, v37, s20, v142
	v_mad_u64_u32 v[44:45], s[22:23], v38, s13, v[42:43]
	v_readlane_b32 s50, v251, 2
	v_readlane_b32 s51, v251, 3
	v_mad_i32_i24 v45, v39, s13, v45
	v_ashrrev_i32_e32 v37, 31, v36
	v_lshl_add_u64 v[46:47], v[142:143], 2, s[50:51]
	v_lshl_add_u64 v[44:45], v[36:37], 2, v[44:45]
	v_readlane_b32 s49, v251, 1
	v_readlane_b32 s52, v251, 4
	v_readlane_b32 s53, v251, 5
	v_readlane_b32 s54, v251, 6
	v_readlane_b32 s55, v251, 7
	v_readlane_b32 s56, v251, 8
	v_readlane_b32 s57, v251, 9
	v_readlane_b32 s58, v251, 10
	v_readlane_b32 s59, v251, 11
	v_readlane_b32 s60, v251, 12
	v_readlane_b32 s61, v251, 13
	v_readlane_b32 s62, v251, 14
	v_readlane_b32 s63, v251, 15
	v_pk_add_f32 v[34:35], v[34:35], v[186:187]
	v_pk_add_f32 v[32:33], v[32:33], v[184:185]
	global_store_dwordx4 v[44:45], v[32:35], off
	v_pk_add_f32 v[30:31], v[30:31], v[190:191]
	v_pk_add_f32 v[28:29], v[28:29], v[188:189]
	global_store_dwordx4 v[44:45], v[28:31], off offset:16
	s_nop 1
	v_lshrrev_b32_e32 v28, 31, v166
	v_ashrrev_i32_e32 v29, 11, v166
	v_add_u32_e32 v29, v29, v28
	v_mul_i32_i24_e32 v30, 0x88, v29
	v_ashrrev_i32_e32 v31, 31, v30
	v_lshl_add_u64 v[30:31], v[30:31], 0, v[40:41]
	v_mad_i32_i24 v28, v29, s20, v165
	v_mad_u64_u32 v[32:33], s[22:23], v30, s13, v[42:43]
	v_mad_i32_i24 v33, v31, s13, v33
	v_ashrrev_i32_e32 v29, 31, v28
	v_lshl_add_u64 v[32:33], v[28:29], 2, v[32:33]
	v_pk_add_f32 v[26:27], v[26:27], v[194:195]
	v_pk_add_f32 v[24:25], v[24:25], v[192:193]
	global_store_dwordx4 v[32:33], v[24:27], off
	v_pk_add_f32 v[22:23], v[22:23], v[198:199]
	v_pk_add_f32 v[20:21], v[20:21], v[196:197]
	global_store_dwordx4 v[32:33], v[20:23], off offset:16
.LBB0_857:
	s_or_b64 exec, exec, s[18:19]
	s_movk_i32 s11, 0xffd8
	v_cmp_gt_i32_e32 vcc, s11, v144
	s_and_saveexec_b64 s[18:19], vcc
	s_cbranch_execz .LBB0_859
	v_add_u32_e32 v21, v168, v167
	v_add_u32_e32 v24, 0xb0, v144
	v_mul_i32_i24_e32 v22, 0x88, v21
	v_ashrrev_i32_e32 v25, 31, v24
	v_ashrrev_i32_e32 v23, 31, v22
	v_lshl_add_u64 v[22:23], v[22:23], 0, v[24:25]
	v_mov_b64_e32 v[26:27], s[6:7]
	v_readlane_b32 s48, v251, 0
	v_mad_i32_i24 v20, v21, s20, v142
	v_mad_u64_u32 v[28:29], s[22:23], v22, s13, v[26:27]
	v_readlane_b32 s50, v251, 2
	v_readlane_b32 s51, v251, 3
	v_mad_i32_i24 v29, v23, s13, v29
	v_ashrrev_i32_e32 v21, 31, v20
	v_lshl_add_u64 v[30:31], v[142:143], 2, s[50:51]
	v_lshl_add_u64 v[28:29], v[20:21], 2, v[28:29]
	v_readlane_b32 s49, v251, 1
	v_readlane_b32 s52, v251, 4
	v_readlane_b32 s53, v251, 5
	v_readlane_b32 s54, v251, 6
	v_readlane_b32 s55, v251, 7
	v_readlane_b32 s56, v251, 8
	v_readlane_b32 s57, v251, 9
	v_readlane_b32 s58, v251, 10
	v_readlane_b32 s59, v251, 11
	v_readlane_b32 s60, v251, 12
	v_readlane_b32 s61, v251, 13
	v_readlane_b32 s62, v251, 14
	v_readlane_b32 s63, v251, 15
	v_pk_add_f32 v[18:19], v[18:19], v[186:187]
	v_pk_add_f32 v[16:17], v[16:17], v[184:185]
	global_store_dwordx4 v[28:29], v[16:19], off
	v_pk_add_f32 v[14:15], v[14:15], v[190:191]
	v_pk_add_f32 v[12:13], v[12:13], v[188:189]
	global_store_dwordx4 v[28:29], v[12:15], off offset:16
	s_nop 1
	v_lshrrev_b32_e32 v12, 31, v166
	v_ashrrev_i32_e32 v13, 11, v166
	v_add_u32_e32 v13, v13, v12
	v_mul_i32_i24_e32 v14, 0x88, v13
	v_ashrrev_i32_e32 v15, 31, v14
	v_lshl_add_u64 v[14:15], v[14:15], 0, v[24:25]
	v_mad_i32_i24 v12, v13, s20, v165
	v_mad_u64_u32 v[16:17], s[22:23], v14, s13, v[26:27]
	v_mad_i32_i24 v17, v15, s13, v17
	v_ashrrev_i32_e32 v13, 31, v12
	v_lshl_add_u64 v[16:17], v[12:13], 2, v[16:17]
	v_pk_add_f32 v[10:11], v[10:11], v[194:195]
	v_pk_add_f32 v[8:9], v[8:9], v[192:193]
	global_store_dwordx4 v[16:17], v[8:11], off
	v_pk_add_f32 v[6:7], v[6:7], v[198:199]
	v_pk_add_f32 v[4:5], v[4:5], v[196:197]
	global_store_dwordx4 v[16:17], v[4:7], off offset:16

;     __device__ __forceinline__ void operator()(const AccT& acc, const pg8::Unit& u, int wr, int wc, int fr, int fq) const {
;     ...
;         for (int ai = 0; ai < 2; ++ai)
; #pragma unroll
;             for (int m = 0; m < 4; ++m) {
;                 const int row = row0 + ai * 128 + m * 16;
;                 if (row < NSEQ) {
; #pragma unroll
;                     for (int bj = 0; bj < 2; ++bj) {
;                         const int c = col0 + bj * 128; const int l = c / 9216, cc = c - l * 9216;
;                         float* p = O + ((size_t)l * NSEQ + row) * 9216 + cc;
;                         *(f32x4*)p = acc[ai][bj][m][0] + *(const f32x4*)(bias + c);
;                         *(f32x4*)(p + 4) = acc[ai][bj][m][1] + *(const f32x4*)(bias + c + 4);
;                     }
;                 }
;             }
.LBB0_863:
	v_add_u32_e32 v69, v168, v167
	v_add_u32_e32 v72, 0x80, v144
	v_mul_i32_i24_e32 v70, 0x88, v69
	v_ashrrev_i32_e32 v73, 31, v72
	v_ashrrev_i32_e32 v71, 31, v70
	v_lshl_add_u64 v[70:71], v[70:71], 0, v[72:73]
	v_mov_b64_e32 v[74:75], s[6:7]
	v_readlane_b32 s48, v251, 0
	v_mad_i32_i24 v68, v69, s20, v142
	v_mad_u64_u32 v[76:77], s[22:23], v70, s13, v[74:75]
	v_readlane_b32 s50, v251, 2
	v_readlane_b32 s51, v251, 3
	v_mad_i32_i24 v77, v71, s13, v77
	v_ashrrev_i32_e32 v69, 31, v68
	v_lshl_add_u64 v[78:79], v[142:143], 2, s[50:51]
	v_lshl_add_u64 v[76:77], v[68:69], 2, v[76:77]
	v_readlane_b32 s49, v251, 1
	v_readlane_b32 s52, v251, 4
	v_readlane_b32 s53, v251, 5
	v_readlane_b32 s54, v251, 6
	v_readlane_b32 s55, v251, 7
	v_readlane_b32 s56, v251, 8
	v_readlane_b32 s57, v251, 9
	v_readlane_b32 s58, v251, 10
	v_readlane_b32 s59, v251, 11
	v_readlane_b32 s60, v251, 12
	v_readlane_b32 s61, v251, 13
	v_readlane_b32 s62, v251, 14
	v_readlane_b32 s63, v251, 15
	v_pk_add_f32 v[66:67], v[66:67], v[186:187]
	v_pk_add_f32 v[64:65], v[64:65], v[184:185]
	global_store_dwordx4 v[76:77], v[64:67], off
	v_pk_add_f32 v[62:63], v[62:63], v[190:191]
	v_pk_add_f32 v[60:61], v[60:61], v[188:189]
	global_store_dwordx4 v[76:77], v[60:63], off offset:16
	s_nop 1
	v_lshrrev_b32_e32 v60, 31, v166
	v_ashrrev_i32_e32 v61, 11, v166
	v_add_u32_e32 v61, v61, v60
	v_mul_i32_i24_e32 v62, 0x88, v61
	v_ashrrev_i32_e32 v63, 31, v62
	v_lshl_add_u64 v[62:63], v[62:63], 0, v[72:73]
	v_mad_i32_i24 v60, v61, s20, v165
	v_mad_u64_u32 v[64:65], s[22:23], v62, s13, v[74:75]
	v_mad_i32_i24 v65, v63, s13, v65
	v_ashrrev_i32_e32 v61, 31, v60
	v_lshl_add_u64 v[64:65], v[60:61], 2, v[64:65]
	v_pk_add_f32 v[58:59], v[58:59], v[194:195]
	v_pk_add_f32 v[56:57], v[56:57], v[192:193]
	global_store_dwordx4 v[64:65], v[56:59], off
	v_pk_add_f32 v[54:55], v[54:55], v[198:199]
	v_pk_add_f32 v[52:53], v[52:53], v[196:197]
	global_store_dwordx4 v[64:65], v[52:55], off offset:16
	s_or_b64 exec, exec, s[18:19]
	v_cmp_gt_i32_e32 vcc, -8, v144
	s_and_saveexec_b64 s[18:19], vcc
	s_cbranch_execnz .LBB0_854
	s_branch .LBB0_855
